# big-GEMM K loop: this k-step's 12 fragment ds_reads issued before the stage ks+2 LDS-DMA (DMA address temp moved to v[248:249])
# speedup vs baseline: 1.0115x; 1.0115x over previous
; #define LDSR(dst, addr, off) asm volatile("ds_read_b128 %0, %1 offset:%2" : "=&v"(dst) : "v"(addr), "n"(off))
; #define LDSR(dst, addr, off) asm volatile("ds_read_b128 %0, %1 offset:%2" : "=&v"(dst) : "v"(addr), "n"(off))
; template <class AP, class BP, class Epi>
; DI void mfma_gemm_big_tile(const AP& aptr, const BP& bptr, int m0, int n0, int K, const Epi& epi, bf16* lds) {
;     ...
;   for (int ks = 0; ks < nk; ++ks) {
;     if (ks + 2 < nk) BG_ISSUE(nxt, ks + 2);
;     const unsigned sa = lbase + (unsigned)(cur * BG_STAGE * 2) + a_off, sb = lbase + (unsigned)(cur * BG_STAGE * 2) + b_off;
;     bf16x8 af[8], bfr[4];
;     LDSR(bfr[0], sb, 0); LDSR(bfr[1], sb, 1024); LDSR(bfr[2], sb, 2048); LDSR(bfr[3], sb, 3072);
;     LDSR(af[0], sa, 0); LDSR(af[1], sa, 1024); LDSR(af[2], sa, 2048); LDSR(af[3], sa, 3072);
;     LDSR(af[4], sa, 4096); LDSR(af[5], sa, 5120); LDSR(af[6], sa, 6144); LDSR(af[7], sa, 7168);
;     asm volatile("s_waitcnt lgkmcnt(0)" : "+v"(af[0]), "+v"(af[1]), "+v"(af[2]), "+v"(af[3]), "+v"(af[4]), "+v"(af[5]), "+v"(af[6]), "+v"(af[7]),
;                  "+v"(bfr[0]), "+v"(bfr[1]), "+v"(bfr[2]), "+v"(bfr[3]) : : "memory");
; #pragma unroll
;     for (int i = 0; i < 8; ++i)
; #pragma unroll
;       for (int j = 0; j < 4; ++j) acc[i][j] = __builtin_amdgcn_mfma_f32_16x16x32_bf16(bfr[j], af[i], acc[i][j], 0, 0, 0);
;     if (ks + 2 < nk) asm volatile("s_waitcnt vmcnt(6)\n\ts_barrier" ::: "memory");
;     else asm volatile("s_waitcnt vmcnt(0)\n\ts_barrier" ::: "memory");
.LBB0_250:
	s_mul_i32 s6, s19, 0x6000
	v_add_u32_e32 v145, s6, v143
	v_add_u32_e32 v159, s6, v144
	ds_read_b128 v[146:149], v159 offset:0
	ds_read_b128 v[150:153], v159 offset:0x400
	ds_read_b128 v[154:157], v159 offset:0x800
	ds_read_b128 v[162:165], v159 offset:0xc00
	ds_read_b128 v[166:169], v145 offset:0
	ds_read_b128 v[182:185], v145 offset:0x400
	ds_read_b128 v[192:195], v145 offset:0x800
	ds_read_b128 v[196:199], v145 offset:0xc00
	ds_read_b128 v[200:203], v145 offset:0x1000
	ds_read_b128 v[204:207], v145 offset:0x1400
	ds_read_b128 v[208:211], v145 offset:0x1800
	ds_read_b128 v[212:215], v145 offset:0x1c00
	s_cmp_gt_u32 s16, 29
	s_cselect_b64 s[4:5], -1, 0
	s_and_b64 vcc, exec, s[4:5]
	s_cbranch_vccnz .LBB0_252
	s_mul_i32 s6, s13, 0x6000
	s_add_i32 s6, s18, s6
	v_lshl_add_u64 v[248:249], s[0:1], 1, v[140:141]
	s_mov_b32 m0, s6
	s_nop 0
	global_load_lds_dwordx4 v[248:249], off
	v_lshl_add_u64 v[248:249], s[0:1], 1, v[138:139]
	s_add_i32 m0, s6, 0x1000
	s_nop 0
	global_load_lds_dwordx4 v[248:249], off
	v_lshl_add_u64 v[248:249], s[0:1], 1, v[136:137]
	s_add_i32 m0, s6, 0x2000
	s_nop 0
	global_load_lds_dwordx4 v[248:249], off
	v_lshl_add_u64 v[248:249], s[0:1], 1, v[134:135]
	s_add_i32 m0, s6, 0x3000
	s_nop 0
	global_load_lds_dwordx4 v[248:249], off
	v_lshl_add_u64 v[248:249], s[0:1], 1, v[132:133]
	s_add_i32 m0, s6, 0x4000
	s_nop 0
	global_load_lds_dwordx4 v[248:249], off
	v_lshl_add_u64 v[248:249], s[0:1], 1, v[130:131]
	s_add_i32 m0, s6, 0x5000
	s_nop 0
	global_load_lds_dwordx4 v[248:249], off
.LBB0_252:
	s_mov_b64 s[6:7], -1
	s_waitcnt lgkmcnt(7)
	s_and_b64 vcc, exec, s[4:5]
	v_mfma_f32_16x16x32_bf16 v[126:129], v[146:149], v[166:169], v[126:129]
	v_mfma_f32_16x16x32_bf16 v[122:125], v[150:153], v[166:169], v[122:125]
	v_mfma_f32_16x16x32_bf16 v[118:121], v[154:157], v[166:169], v[118:121]
	v_mfma_f32_16x16x32_bf16 v[114:117], v[162:165], v[166:169], v[114:117]
	s_waitcnt lgkmcnt(6)
	v_mfma_f32_16x16x32_bf16 v[110:113], v[146:149], v[182:185], v[110:113]
	v_mfma_f32_16x16x32_bf16 v[106:109], v[150:153], v[182:185], v[106:109]
	v_mfma_f32_16x16x32_bf16 v[102:105], v[154:157], v[182:185], v[102:105]
	v_mfma_f32_16x16x32_bf16 v[98:101], v[162:165], v[182:185], v[98:101]
	s_waitcnt lgkmcnt(5)
	v_mfma_f32_16x16x32_bf16 v[94:97], v[146:149], v[192:195], v[94:97]
	v_mfma_f32_16x16x32_bf16 v[90:93], v[150:153], v[192:195], v[90:93]
	v_mfma_f32_16x16x32_bf16 v[86:89], v[154:157], v[192:195], v[86:89]
	v_mfma_f32_16x16x32_bf16 v[82:85], v[162:165], v[192:195], v[82:85]
	s_waitcnt lgkmcnt(4)
	v_mfma_f32_16x16x32_bf16 v[78:81], v[146:149], v[196:199], v[78:81]
	v_mfma_f32_16x16x32_bf16 v[74:77], v[150:153], v[196:199], v[74:77]
	v_mfma_f32_16x16x32_bf16 v[70:73], v[154:157], v[196:199], v[70:73]
	v_mfma_f32_16x16x32_bf16 v[66:69], v[162:165], v[196:199], v[66:69]
	s_waitcnt lgkmcnt(3)
	v_mfma_f32_16x16x32_bf16 v[62:65], v[146:149], v[200:203], v[62:65]
	v_mfma_f32_16x16x32_bf16 v[58:61], v[150:153], v[200:203], v[58:61]
	v_mfma_f32_16x16x32_bf16 v[54:57], v[154:157], v[200:203], v[54:57]
	v_mfma_f32_16x16x32_bf16 v[50:53], v[162:165], v[200:203], v[50:53]
	s_waitcnt lgkmcnt(2)
	v_mfma_f32_16x16x32_bf16 v[46:49], v[146:149], v[204:207], v[46:49]
	v_mfma_f32_16x16x32_bf16 v[42:45], v[150:153], v[204:207], v[42:45]
	v_mfma_f32_16x16x32_bf16 v[38:41], v[154:157], v[204:207], v[38:41]
	v_mfma_f32_16x16x32_bf16 v[34:37], v[162:165], v[204:207], v[34:37]
	s_waitcnt lgkmcnt(1)
	v_mfma_f32_16x16x32_bf16 v[30:33], v[146:149], v[208:211], v[30:33]
	v_mfma_f32_16x16x32_bf16 v[26:29], v[150:153], v[208:211], v[26:29]
	v_mfma_f32_16x16x32_bf16 v[22:25], v[154:157], v[208:211], v[22:25]
	v_mfma_f32_16x16x32_bf16 v[18:21], v[162:165], v[208:211], v[18:21]
	s_waitcnt lgkmcnt(0)
	v_mfma_f32_16x16x32_bf16 v[14:17], v[146:149], v[212:215], v[14:17]
	v_mfma_f32_16x16x32_bf16 v[10:13], v[150:153], v[212:215], v[10:13]
	v_mfma_f32_16x16x32_bf16 v[6:9], v[154:157], v[212:215], v[6:9]
	v_mfma_f32_16x16x32_bf16 v[2:5], v[162:165], v[212:215], v[2:5]
	s_cbranch_vccz .LBB0_254
	s_waitcnt vmcnt(0)
	s_barrier
	s_mov_b64 s[6:7], 0

; #define LDSR(dst, addr, off) asm volatile("ds_read_b128 %0, %1 offset:%2" : "=&v"(dst) : "v"(addr), "n"(off))
; #define LDSR(dst, addr, off) asm volatile("ds_read_b128 %0, %1 offset:%2" : "=&v"(dst) : "v"(addr), "n"(off))
; template <class AP, class BP, class Epi>
; DI void mfma_gemm_big_tile(const AP& aptr, const BP& bptr, int m0, int n0, int K, const Epi& epi, bf16* lds) {
;     ...
;   for (int ks = 0; ks < nk; ++ks) {
;     if (ks + 2 < nk) BG_ISSUE(nxt, ks + 2);
;     const unsigned sa = lbase + (unsigned)(cur * BG_STAGE * 2) + a_off, sb = lbase + (unsigned)(cur * BG_STAGE * 2) + b_off;
;     bf16x8 af[8], bfr[4];
;     LDSR(bfr[0], sb, 0); LDSR(bfr[1], sb, 1024); LDSR(bfr[2], sb, 2048); LDSR(bfr[3], sb, 3072);
;     LDSR(af[0], sa, 0); LDSR(af[1], sa, 1024); LDSR(af[2], sa, 2048); LDSR(af[3], sa, 3072);
;     LDSR(af[4], sa, 4096); LDSR(af[5], sa, 5120); LDSR(af[6], sa, 6144); LDSR(af[7], sa, 7168);
;     asm volatile("s_waitcnt lgkmcnt(0)" : "+v"(af[0]), "+v"(af[1]), "+v"(af[2]), "+v"(af[3]), "+v"(af[4]), "+v"(af[5]), "+v"(af[6]), "+v"(af[7]),
;                  "+v"(bfr[0]), "+v"(bfr[1]), "+v"(bfr[2]), "+v"(bfr[3]) : : "memory");
; #pragma unroll
;     for (int i = 0; i < 8; ++i)
; #pragma unroll
;       for (int j = 0; j < 4; ++j) acc[i][j] = __builtin_amdgcn_mfma_f32_16x16x32_bf16(bfr[j], af[i], acc[i][j], 0, 0, 0);
;     if (ks + 2 < nk) asm volatile("s_waitcnt vmcnt(6)\n\ts_barrier" ::: "memory");
;     else asm volatile("s_waitcnt vmcnt(0)\n\ts_barrier" ::: "memory");
.LBB0_510:
	s_mul_i32 s6, s18, 0x6000
	v_add_u32_e32 v145, s6, v143
	v_add_u32_e32 v159, s6, v144
	ds_read_b128 v[146:149], v159 offset:0
	ds_read_b128 v[150:153], v159 offset:0x400
	ds_read_b128 v[154:157], v159 offset:0x800
	ds_read_b128 v[162:165], v159 offset:0xc00
	ds_read_b128 v[166:169], v145 offset:0
	ds_read_b128 v[192:195], v145 offset:0x400
	ds_read_b128 v[196:199], v145 offset:0x800
	ds_read_b128 v[200:203], v145 offset:0xc00
	ds_read_b128 v[204:207], v145 offset:0x1000
	ds_read_b128 v[208:211], v145 offset:0x1400
	ds_read_b128 v[212:215], v145 offset:0x1800
	ds_read_b128 v[216:219], v145 offset:0x1c00
	s_cmp_gt_u32 s15, 29
	s_cselect_b64 s[4:5], -1, 0
	s_and_b64 vcc, exec, s[4:5]
	s_cbranch_vccnz .LBB0_512
	s_mul_i32 s6, s13, 0x6000
	s_add_i32 s6, s17, s6
	v_lshl_add_u64 v[248:249], s[0:1], 1, v[140:141]
	s_mov_b32 m0, s6
	s_nop 0
	global_load_lds_dwordx4 v[248:249], off
	v_lshl_add_u64 v[248:249], s[0:1], 1, v[138:139]
	s_add_i32 m0, s6, 0x1000
	s_nop 0
	global_load_lds_dwordx4 v[248:249], off
	v_lshl_add_u64 v[248:249], s[0:1], 1, v[136:137]
	s_add_i32 m0, s6, 0x2000
	s_nop 0
	global_load_lds_dwordx4 v[248:249], off
	v_lshl_add_u64 v[248:249], s[0:1], 1, v[134:135]
	s_add_i32 m0, s6, 0x3000
	s_nop 0
	global_load_lds_dwordx4 v[248:249], off
	v_lshl_add_u64 v[248:249], s[0:1], 1, v[132:133]
	s_add_i32 m0, s6, 0x4000
	s_nop 0
	global_load_lds_dwordx4 v[248:249], off
	v_lshl_add_u64 v[248:249], s[0:1], 1, v[130:131]
	s_add_i32 m0, s6, 0x5000
	s_nop 0
	global_load_lds_dwordx4 v[248:249], off
.LBB0_512:
	s_mov_b64 s[6:7], -1
	s_waitcnt lgkmcnt(7)
	s_and_b64 vcc, exec, s[4:5]
	v_mfma_f32_16x16x32_bf16 v[126:129], v[146:149], v[166:169], v[126:129]
	v_mfma_f32_16x16x32_bf16 v[122:125], v[150:153], v[166:169], v[122:125]
	v_mfma_f32_16x16x32_bf16 v[118:121], v[154:157], v[166:169], v[118:121]
	v_mfma_f32_16x16x32_bf16 v[114:117], v[162:165], v[166:169], v[114:117]
	s_waitcnt lgkmcnt(6)
	v_mfma_f32_16x16x32_bf16 v[110:113], v[146:149], v[192:195], v[110:113]
	v_mfma_f32_16x16x32_bf16 v[106:109], v[150:153], v[192:195], v[106:109]
	v_mfma_f32_16x16x32_bf16 v[102:105], v[154:157], v[192:195], v[102:105]
	v_mfma_f32_16x16x32_bf16 v[98:101], v[162:165], v[192:195], v[98:101]
	s_waitcnt lgkmcnt(5)
	v_mfma_f32_16x16x32_bf16 v[94:97], v[146:149], v[196:199], v[94:97]
	v_mfma_f32_16x16x32_bf16 v[90:93], v[150:153], v[196:199], v[90:93]
	v_mfma_f32_16x16x32_bf16 v[86:89], v[154:157], v[196:199], v[86:89]
	v_mfma_f32_16x16x32_bf16 v[82:85], v[162:165], v[196:199], v[82:85]
	s_waitcnt lgkmcnt(4)
	v_mfma_f32_16x16x32_bf16 v[78:81], v[146:149], v[200:203], v[78:81]
	v_mfma_f32_16x16x32_bf16 v[74:77], v[150:153], v[200:203], v[74:77]
	v_mfma_f32_16x16x32_bf16 v[70:73], v[154:157], v[200:203], v[70:73]
	v_mfma_f32_16x16x32_bf16 v[66:69], v[162:165], v[200:203], v[66:69]
	s_waitcnt lgkmcnt(3)
	v_mfma_f32_16x16x32_bf16 v[62:65], v[146:149], v[204:207], v[62:65]
	v_mfma_f32_16x16x32_bf16 v[58:61], v[150:153], v[204:207], v[58:61]
	v_mfma_f32_16x16x32_bf16 v[54:57], v[154:157], v[204:207], v[54:57]
	v_mfma_f32_16x16x32_bf16 v[50:53], v[162:165], v[204:207], v[50:53]
	s_waitcnt lgkmcnt(2)
	v_mfma_f32_16x16x32_bf16 v[46:49], v[146:149], v[208:211], v[46:49]
	v_mfma_f32_16x16x32_bf16 v[42:45], v[150:153], v[208:211], v[42:45]
	v_mfma_f32_16x16x32_bf16 v[38:41], v[154:157], v[208:211], v[38:41]
	v_mfma_f32_16x16x32_bf16 v[34:37], v[162:165], v[208:211], v[34:37]
	s_waitcnt lgkmcnt(1)
	v_mfma_f32_16x16x32_bf16 v[30:33], v[146:149], v[212:215], v[30:33]
	v_mfma_f32_16x16x32_bf16 v[26:29], v[150:153], v[212:215], v[26:29]
	v_mfma_f32_16x16x32_bf16 v[22:25], v[154:157], v[212:215], v[22:25]
	v_mfma_f32_16x16x32_bf16 v[18:21], v[162:165], v[212:215], v[18:21]
	s_waitcnt lgkmcnt(0)
	v_mfma_f32_16x16x32_bf16 v[14:17], v[146:149], v[216:219], v[14:17]
	v_mfma_f32_16x16x32_bf16 v[10:13], v[150:153], v[216:219], v[10:13]
	v_mfma_f32_16x16x32_bf16 v[6:9], v[154:157], v[216:219], v[6:9]
	v_mfma_f32_16x16x32_bf16 v[2:5], v[162:165], v[216:219], v[2:5]
	s_cbranch_vccz .LBB0_514
	s_waitcnt vmcnt(0)
	s_barrier
	s_mov_b64 s[6:7], 0

; #define LDSR(dst, addr, off) asm volatile("ds_read_b128 %0, %1 offset:%2" : "=&v"(dst) : "v"(addr), "n"(off))
; #define LDSR(dst, addr, off) asm volatile("ds_read_b128 %0, %1 offset:%2" : "=&v"(dst) : "v"(addr), "n"(off))
; template <class AP, class BP, class Epi>
; DI void mfma_gemm_big_tile(const AP& aptr, const BP& bptr, int m0, int n0, int K, const Epi& epi, bf16* lds) {
;     ...
;   for (int ks = 0; ks < nk; ++ks) {
;     if (ks + 2 < nk) BG_ISSUE(nxt, ks + 2);
;     const unsigned sa = lbase + (unsigned)(cur * BG_STAGE * 2) + a_off, sb = lbase + (unsigned)(cur * BG_STAGE * 2) + b_off;
;     bf16x8 af[8], bfr[4];
;     LDSR(bfr[0], sb, 0); LDSR(bfr[1], sb, 1024); LDSR(bfr[2], sb, 2048); LDSR(bfr[3], sb, 3072);
;     LDSR(af[0], sa, 0); LDSR(af[1], sa, 1024); LDSR(af[2], sa, 2048); LDSR(af[3], sa, 3072);
;     LDSR(af[4], sa, 4096); LDSR(af[5], sa, 5120); LDSR(af[6], sa, 6144); LDSR(af[7], sa, 7168);
;     asm volatile("s_waitcnt lgkmcnt(0)" : "+v"(af[0]), "+v"(af[1]), "+v"(af[2]), "+v"(af[3]), "+v"(af[4]), "+v"(af[5]), "+v"(af[6]), "+v"(af[7]),
;                  "+v"(bfr[0]), "+v"(bfr[1]), "+v"(bfr[2]), "+v"(bfr[3]) : : "memory");
; #pragma unroll
;     for (int i = 0; i < 8; ++i)
; #pragma unroll
;       for (int j = 0; j < 4; ++j) acc[i][j] = __builtin_amdgcn_mfma_f32_16x16x32_bf16(bfr[j], af[i], acc[i][j], 0, 0, 0);
;     if (ks + 2 < nk) asm volatile("s_waitcnt vmcnt(6)\n\ts_barrier" ::: "memory");
;     else asm volatile("s_waitcnt vmcnt(0)\n\ts_barrier" ::: "memory");
.LBB0_1107:
	s_mul_i32 s10, s21, 0x6000
	v_add_u32_e32 v145, s10, v143
	v_add_u32_e32 v159, s10, v144
	ds_read_b128 v[146:149], v159 offset:0
	ds_read_b128 v[150:153], v159 offset:0x400
	ds_read_b128 v[154:157], v159 offset:0x800
	ds_read_b128 v[162:165], v159 offset:0xc00
	ds_read_b128 v[166:169], v145 offset:0
	ds_read_b128 v[182:185], v145 offset:0x400
	ds_read_b128 v[192:195], v145 offset:0x800
	ds_read_b128 v[196:199], v145 offset:0xc00
	ds_read_b128 v[200:203], v145 offset:0x1000
	ds_read_b128 v[204:207], v145 offset:0x1400
	ds_read_b128 v[208:211], v145 offset:0x1800
	ds_read_b128 v[212:215], v145 offset:0x1c00
	s_cmp_gt_u32 s18, 29
	s_cselect_b64 s[8:9], -1, 0
	s_and_b64 vcc, exec, s[8:9]
	s_cbranch_vccnz .LBB0_1109
	s_mul_i32 s10, s17, 0x6000
	s_add_i32 s10, s20, s10
	v_lshl_add_u64 v[248:249], s[0:1], 1, v[140:141]
	s_mov_b32 m0, s10
	s_nop 0
	global_load_lds_dwordx4 v[248:249], off
	v_lshl_add_u64 v[248:249], s[0:1], 1, v[138:139]
	s_add_i32 m0, s10, 0x1000
	s_nop 0
	global_load_lds_dwordx4 v[248:249], off
	v_lshl_add_u64 v[248:249], s[0:1], 1, v[136:137]
	s_add_i32 m0, s10, 0x2000
	s_nop 0
	global_load_lds_dwordx4 v[248:249], off
	v_lshl_add_u64 v[248:249], s[0:1], 1, v[134:135]
	s_add_i32 m0, s10, 0x3000
	s_nop 0
	global_load_lds_dwordx4 v[248:249], off
	v_lshl_add_u64 v[248:249], v[132:133], 0, s[0:1]
	s_add_i32 m0, s10, 0x4000
	s_nop 0
	global_load_lds_dwordx4 v[248:249], off
	v_lshl_add_u64 v[248:249], v[130:131], 0, s[0:1]
	s_add_i32 m0, s10, 0x5000
	s_nop 0
	global_load_lds_dwordx4 v[248:249], off
.LBB0_1109:
	s_mov_b64 s[10:11], -1
	s_waitcnt lgkmcnt(7)
	s_and_b64 vcc, exec, s[8:9]
	v_mfma_f32_16x16x32_bf16 v[126:129], v[146:149], v[166:169], v[126:129]
	v_mfma_f32_16x16x32_bf16 v[122:125], v[150:153], v[166:169], v[122:125]
	v_mfma_f32_16x16x32_bf16 v[118:121], v[154:157], v[166:169], v[118:121]
	v_mfma_f32_16x16x32_bf16 v[114:117], v[162:165], v[166:169], v[114:117]
	s_waitcnt lgkmcnt(6)
	v_mfma_f32_16x16x32_bf16 v[110:113], v[146:149], v[182:185], v[110:113]
	v_mfma_f32_16x16x32_bf16 v[106:109], v[150:153], v[182:185], v[106:109]
	v_mfma_f32_16x16x32_bf16 v[102:105], v[154:157], v[182:185], v[102:105]
	v_mfma_f32_16x16x32_bf16 v[98:101], v[162:165], v[182:185], v[98:101]
	s_waitcnt lgkmcnt(5)
	v_mfma_f32_16x16x32_bf16 v[94:97], v[146:149], v[192:195], v[94:97]
	v_mfma_f32_16x16x32_bf16 v[90:93], v[150:153], v[192:195], v[90:93]
	v_mfma_f32_16x16x32_bf16 v[86:89], v[154:157], v[192:195], v[86:89]
	v_mfma_f32_16x16x32_bf16 v[82:85], v[162:165], v[192:195], v[82:85]
	s_waitcnt lgkmcnt(4)
	v_mfma_f32_16x16x32_bf16 v[78:81], v[146:149], v[196:199], v[78:81]
	v_mfma_f32_16x16x32_bf16 v[74:77], v[150:153], v[196:199], v[74:77]
	v_mfma_f32_16x16x32_bf16 v[70:73], v[154:157], v[196:199], v[70:73]
	v_mfma_f32_16x16x32_bf16 v[66:69], v[162:165], v[196:199], v[66:69]
	s_waitcnt lgkmcnt(3)
	v_mfma_f32_16x16x32_bf16 v[62:65], v[146:149], v[200:203], v[62:65]
	v_mfma_f32_16x16x32_bf16 v[58:61], v[150:153], v[200:203], v[58:61]
	v_mfma_f32_16x16x32_bf16 v[54:57], v[154:157], v[200:203], v[54:57]
	v_mfma_f32_16x16x32_bf16 v[50:53], v[162:165], v[200:203], v[50:53]
	s_waitcnt lgkmcnt(2)
	v_mfma_f32_16x16x32_bf16 v[46:49], v[146:149], v[204:207], v[46:49]
	v_mfma_f32_16x16x32_bf16 v[42:45], v[150:153], v[204:207], v[42:45]
	v_mfma_f32_16x16x32_bf16 v[38:41], v[154:157], v[204:207], v[38:41]
	v_mfma_f32_16x16x32_bf16 v[34:37], v[162:165], v[204:207], v[34:37]
	s_waitcnt lgkmcnt(1)
	v_mfma_f32_16x16x32_bf16 v[30:33], v[146:149], v[208:211], v[30:33]
	v_mfma_f32_16x16x32_bf16 v[26:29], v[150:153], v[208:211], v[26:29]
	v_mfma_f32_16x16x32_bf16 v[22:25], v[154:157], v[208:211], v[22:25]
	v_mfma_f32_16x16x32_bf16 v[18:21], v[162:165], v[208:211], v[18:21]
	s_waitcnt lgkmcnt(0)
	v_mfma_f32_16x16x32_bf16 v[14:17], v[146:149], v[212:215], v[14:17]
	v_mfma_f32_16x16x32_bf16 v[10:13], v[150:153], v[212:215], v[10:13]
	v_mfma_f32_16x16x32_bf16 v[6:9], v[154:157], v[212:215], v[6:9]
	v_mfma_f32_16x16x32_bf16 v[2:5], v[162:165], v[212:215], v[2:5]
	s_cbranch_vccz .LBB0_1111
	s_waitcnt vmcnt(0)
	s_barrier
	s_mov_b64 s[10:11], 0
